# FFN-in K-loop: LDS fragment base addresses precomputed per phase (no per-phase VALU address adds) on top of scalar-base LDS-DMA loads
# speedup vs baseline: 1.0132x; 1.0009x over previous
.LBB0_148:
	s_add_u32 s16, s78, 0x15000000
	s_addc_u32 s17, s79, 0
	s_lshl_b32 s0, s0, 5
	s_and_b32 s0, s0, 0x60
	s_add_i32 m0, s41, 0x18000
	v_lshl_add_u64 v[136:137], v[136:137], 0, s[70:71]
	s_lshl_b32 s4, s1, 13
	s_lshl_b32 s20, s0, 7
	s_waitcnt vmcnt(2)
	s_barrier
	global_load_lds_dwordx4 v[136:137], off
	v_lshl_add_u64 v[134:135], v[134:135], 0, s[70:71]
	s_add_i32 m0, s41, 0x1a000
	s_add_i32 s52, s41, 0x8000
	s_add_i32 s53, s41, 0xa000
	global_load_lds_dwordx4 v[134:135], off
	v_lshl_add_u64 v[126:127], v[126:127], 0, s[70:71]
	s_mov_b32 m0, s52
	s_add_u32 s18, s28, 0x40080
	global_load_lds_dwordx4 v[126:127], off
	v_lshl_add_u64 v[126:127], v[128:129], 0, s[70:71]
	s_mov_b32 m0, s53
	s_addc_u32 s19, s29, 0
	global_load_lds_dwordx4 v[126:127], off
	s_add_i32 m0, s41, 0x1c000
	v_lshl_add_u64 v[126:127], s[18:19], 0, v[48:49]
	global_load_lds_dwordx4 v[126:127], off
	v_lshl_add_u64 v[126:127], s[18:19], 0, v[158:159]
	s_add_i32 m0, s41, 0x1e000
	v_mov_b32_e32 v163, v49
	global_load_lds_dwordx4 v[126:127], off
	v_lshrrev_b32_e32 v127, 1, v237
	v_and_b32_e32 v128, 24, v127
	v_and_b32_e32 v126, 15, v237
	v_lshlrev_b32_e32 v127, 1, v128
	v_lshl_or_b32 v166, s1, 6, v126
	v_lshl_or_b32 v126, v126, 6, v127
	v_lshlrev_b32_e32 v127, 2, v237
	v_and_b32_e32 v127, 32, v127
	v_bitop3_b32 v129, v126, s4, v127 bitop3:0xde
	v_bitop3_b32 v167, s20, v126, v127 bitop3:0xf6
	v_add_u32_e32 v222, s62, v167
	v_add_u32_e32 v223, 0x14000, v167
	v_add_u32_e32 v224, 0x18000, v167
	v_add_u32_e32 v225, 0x1c000, v167
	v_lshlrev_b32_e32 v126, 4, v236
	v_mov_b32_e32 v127, v49
	v_lshl_add_u64 v[160:161], s[8:9], 0, v[126:127]
	v_lshlrev_b32_e32 v126, 14, v138
	v_and_b32_e32 v126, 0xffff8000, v126
	v_lshl_add_u32 v126, v139, 11, v126
	v_and_b32_e32 v127, 1, v138
	v_lshl_or_b32 v126, v127, 6, v126
	v_lshl_add_u32 v162, v140, 1, v126
	v_lshlrev_b32_e32 v126, 14, v141
	s_add_i32 s1, 0, 0x22000
	v_and_b32_e32 v126, 0xffff8000, v126
	v_readlane_b32 s8, v254, 32
	s_waitcnt vmcnt(6)
	s_add_i32 s82, s1, s36
	v_lshl_add_u32 v126, v142, 11, v126
	v_and_b32_e32 v127, 1, v141
	v_readlane_b32 s9, v254, 33
	s_cmpk_lt_u32 s83, 0x100
	v_or_b32_e32 v168, s0, v128
	v_lshl_or_b32 v126, v127, 6, v126
	s_mov_b32 s0, s8
	v_readlane_b32 s8, v254, 28
	s_cselect_b64 s[18:19], -1, 0
	s_andn2_b32 s83, s83, 63
	s_ashr_i32 s84, s3, 31
	v_lshl_add_u32 v169, v166, 4, s1
	v_lshl_add_u32 v164, v143, 1, v126
	v_mov_b32_e32 v165, v49
	s_mov_b32 s1, 0
	v_add_u32_e32 v170, 0, v129
	s_mov_b32 s4, s8
	s_barrier
	v_readlane_b32 s9, v254, 29
	s_branch .LBB0_151

.LBB0_158:
	s_add_u32 s28, s30, 0xfffc0080
	s_addc_u32 s29, s31, -1
	s_cmp_eq_u32 s54, 12
	s_cselect_b32 s35, s23, s29
	s_cselect_b32 s34, s33, s28
	s_cselect_b32 s29, s21, s46
	s_cselect_b32 s28, s44, s45
	s_add_i32 s55, 0, 0x14000
	ds_read_b128 v[126:129], v222
	ds_read_b128 v[134:137], v222 offset:1024
	ds_read_b128 v[138:141], v222 offset:2048
	ds_read_b128 v[142:145], v222 offset:3072
	ds_read_b128 v[146:149], v223
	ds_read_b128 v[150:153], v223 offset:1024
	ds_read_b128 v[172:175], v223 offset:2048
	ds_read_b128 v[176:179], v223 offset:3072
	s_add_i32 m0, s41, 0xc000
	ds_read_b128 v[180:183], v170
	ds_read_b128 v[184:187], v170 offset:1024
	ds_read_b128 v[198:201], v170 offset:2048
	ds_read_b128 v[202:205], v170 offset:3072
	ds_read_b128 v[206:209], v170 offset:4096
	ds_read_b128 v[210:213], v170 offset:5120
	ds_read_b128 v[214:217], v170 offset:6144
	ds_read_b128 v[218:221], v170 offset:7168
	global_load_lds_dwordx4 v162, s[30:31]
	s_add_i32 m0, s41, 0xe000
	s_nop 0
	global_load_lds_dwordx4 v164, s[30:31]
	s_waitcnt vmcnt(8)
	s_waitcnt lgkmcnt(0)
	s_barrier
	s_setprio 1
	s_waitcnt lgkmcnt(0)
	v_mfma_f32_16x16x32_bf16 v[122:125], v[126:129], v[180:183], v[122:125]
	v_mfma_f32_16x16x32_bf16 v[114:117], v[138:141], v[180:183], v[114:117]
	v_mfma_f32_16x16x32_bf16 v[106:109], v[126:129], v[198:201], v[106:109]
	v_mfma_f32_16x16x32_bf16 v[98:101], v[138:141], v[198:201], v[98:101]
	v_mfma_f32_16x16x32_bf16 v[90:93], v[126:129], v[206:209], v[90:93]
	v_mfma_f32_16x16x32_bf16 v[82:85], v[138:141], v[206:209], v[82:85]
	v_mfma_f32_16x16x32_bf16 v[74:77], v[126:129], v[214:217], v[74:77]
	v_mfma_f32_16x16x32_bf16 v[66:69], v[138:141], v[214:217], v[66:69]
	v_mfma_f32_16x16x32_bf16 v[122:125], v[134:137], v[184:187], v[122:125]
	v_mfma_f32_16x16x32_bf16 v[114:117], v[142:145], v[184:187], v[114:117]
	v_mfma_f32_16x16x32_bf16 v[106:109], v[134:137], v[202:205], v[106:109]
	v_mfma_f32_16x16x32_bf16 v[98:101], v[142:145], v[202:205], v[98:101]
	v_mfma_f32_16x16x32_bf16 v[90:93], v[134:137], v[210:213], v[90:93]
	v_mfma_f32_16x16x32_bf16 v[82:85], v[142:145], v[210:213], v[82:85]
	v_mfma_f32_16x16x32_bf16 v[74:77], v[134:137], v[218:221], v[74:77]
	v_mfma_f32_16x16x32_bf16 v[66:69], v[142:145], v[218:221], v[66:69]
	s_setprio 0
	s_setprio 1
	v_mfma_f32_16x16x32_bf16 v[130:133], v[146:149], v[180:183], v[130:133]
	v_mfma_f32_16x16x32_bf16 v[118:121], v[172:175], v[180:183], v[118:121]
	v_mfma_f32_16x16x32_bf16 v[110:113], v[146:149], v[198:201], v[110:113]
	v_mfma_f32_16x16x32_bf16 v[102:105], v[172:175], v[198:201], v[102:105]
	v_mfma_f32_16x16x32_bf16 v[94:97], v[146:149], v[206:209], v[94:97]
	v_mfma_f32_16x16x32_bf16 v[86:89], v[172:175], v[206:209], v[86:89]
	v_mfma_f32_16x16x32_bf16 v[78:81], v[146:149], v[214:217], v[78:81]
	v_mfma_f32_16x16x32_bf16 v[70:73], v[172:175], v[214:217], v[70:73]
	v_mfma_f32_16x16x32_bf16 v[130:133], v[150:153], v[184:187], v[130:133]
	v_mfma_f32_16x16x32_bf16 v[118:121], v[176:179], v[184:187], v[118:121]
	v_mfma_f32_16x16x32_bf16 v[110:113], v[150:153], v[202:205], v[110:113]
	v_mfma_f32_16x16x32_bf16 v[102:105], v[176:179], v[202:205], v[102:105]
	v_mfma_f32_16x16x32_bf16 v[94:97], v[150:153], v[210:213], v[94:97]
	v_mfma_f32_16x16x32_bf16 v[86:89], v[176:179], v[210:213], v[86:89]
	v_mfma_f32_16x16x32_bf16 v[78:81], v[150:153], v[218:221], v[78:81]
	v_mfma_f32_16x16x32_bf16 v[70:73], v[176:179], v[218:221], v[70:73]
	s_setprio 0
	s_barrier
	s_add_i32 s56, s62, s36
	s_mov_b32 m0, s56
	ds_read_b128 v[180:183], v170 offset:16384
	ds_read_b128 v[184:187], v170 offset:17408
	ds_read_b128 v[198:201], v170 offset:18432
	ds_read_b128 v[202:205], v170 offset:19456
	ds_read_b128 v[206:209], v170 offset:20480
	ds_read_b128 v[210:213], v170 offset:21504
	ds_read_b128 v[214:217], v170 offset:22528
	ds_read_b128 v[218:221], v170 offset:23552
	global_load_lds_dwordx4 v48, s[28:29]
	s_add_i32 m0, s56, 0x2000
	s_add_u32 s68, s28, 0x40000
	s_addc_u32 s69, s29, 0
	s_add_i32 s55, s55, s36
	global_load_lds_dwordx4 v158, s[28:29]
	s_mov_b32 m0, s55
	s_nop 0
	global_load_lds_dwordx4 v48, s[68:69]
	s_add_i32 m0, s55, 0x2000
	s_nop 0
	global_load_lds_dwordx4 v158, s[68:69]
	s_mov_b32 m0, s41
	s_nop 0
	global_load_lds_dwordx4 v154, s[34:35]
	s_mov_b32 m0, s48
	s_nop 0
	global_load_lds_dwordx4 v156, s[34:35]
	s_waitcnt vmcnt(8)
	s_waitcnt lgkmcnt(0)
	s_barrier
	s_setprio 1
	s_waitcnt lgkmcnt(0)
	v_mfma_f32_16x16x32_bf16 v[58:61], v[126:129], v[180:183], v[58:61]
	v_mfma_f32_16x16x32_bf16 v[50:53], v[138:141], v[180:183], v[50:53]
	v_mfma_f32_16x16x32_bf16 v[40:43], v[126:129], v[198:201], v[40:43]
	v_mfma_f32_16x16x32_bf16 v[32:35], v[138:141], v[198:201], v[32:35]
	v_mfma_f32_16x16x32_bf16 v[24:27], v[126:129], v[206:209], v[24:27]
	v_mfma_f32_16x16x32_bf16 v[16:19], v[138:141], v[206:209], v[16:19]
	v_mfma_f32_16x16x32_bf16 v[8:11], v[126:129], v[214:217], v[8:11]
	v_mfma_f32_16x16x32_bf16 v[0:3], v[138:141], v[214:217], v[0:3]
	v_mfma_f32_16x16x32_bf16 v[58:61], v[134:137], v[184:187], v[58:61]
	v_mfma_f32_16x16x32_bf16 v[50:53], v[142:145], v[184:187], v[50:53]
	v_mfma_f32_16x16x32_bf16 v[40:43], v[134:137], v[202:205], v[40:43]
	v_mfma_f32_16x16x32_bf16 v[32:35], v[142:145], v[202:205], v[32:35]
	v_mfma_f32_16x16x32_bf16 v[24:27], v[134:137], v[210:213], v[24:27]
	v_mfma_f32_16x16x32_bf16 v[16:19], v[142:145], v[210:213], v[16:19]
	v_mfma_f32_16x16x32_bf16 v[8:11], v[134:137], v[218:221], v[8:11]
	v_mfma_f32_16x16x32_bf16 v[0:3], v[142:145], v[218:221], v[0:3]
	s_setprio 0
	s_setprio 1
	v_mfma_f32_16x16x32_bf16 v[62:65], v[146:149], v[180:183], v[62:65]
	v_mfma_f32_16x16x32_bf16 v[54:57], v[172:175], v[180:183], v[54:57]
	v_mfma_f32_16x16x32_bf16 v[44:47], v[146:149], v[198:201], v[44:47]
	v_mfma_f32_16x16x32_bf16 v[36:39], v[172:175], v[198:201], v[36:39]
	v_mfma_f32_16x16x32_bf16 v[28:31], v[146:149], v[206:209], v[28:31]
	v_mfma_f32_16x16x32_bf16 v[20:23], v[172:175], v[206:209], v[20:23]
	v_mfma_f32_16x16x32_bf16 v[12:15], v[146:149], v[214:217], v[12:15]
	v_mfma_f32_16x16x32_bf16 v[4:7], v[172:175], v[214:217], v[4:7]
	v_mfma_f32_16x16x32_bf16 v[62:65], v[150:153], v[184:187], v[62:65]
	v_mfma_f32_16x16x32_bf16 v[54:57], v[176:179], v[184:187], v[54:57]
	v_mfma_f32_16x16x32_bf16 v[44:47], v[150:153], v[202:205], v[44:47]
	v_mfma_f32_16x16x32_bf16 v[36:39], v[176:179], v[202:205], v[36:39]
	v_mfma_f32_16x16x32_bf16 v[28:31], v[150:153], v[210:213], v[28:31]
	v_mfma_f32_16x16x32_bf16 v[20:23], v[176:179], v[210:213], v[20:23]
	v_mfma_f32_16x16x32_bf16 v[12:15], v[150:153], v[218:221], v[12:15]
	v_mfma_f32_16x16x32_bf16 v[4:7], v[176:179], v[218:221], v[4:7]
	s_setprio 0
	s_barrier
	s_add_i32 s55, 0, 0x18000
	s_add_i32 s56, 0, 0x1c000
	ds_read_b128 v[126:129], v224
	ds_read_b128 v[134:137], v224 offset:1024
	ds_read_b128 v[138:141], v224 offset:2048
	ds_read_b128 v[142:145], v224 offset:3072
	ds_read_b128 v[146:149], v225
	ds_read_b128 v[150:153], v225 offset:1024
	ds_read_b128 v[172:175], v225 offset:2048
	ds_read_b128 v[176:179], v225 offset:3072
	s_add_u32 s34, s34, 0x40000
	s_addc_u32 s35, s35, 0
	s_mov_b32 m0, s49
	ds_read_b128 v[180:183], v170 offset:32768
	ds_read_b128 v[184:187], v170 offset:33792
	ds_read_b128 v[198:201], v170 offset:34816
	ds_read_b128 v[202:205], v170 offset:35840
	ds_read_b128 v[206:209], v170 offset:36864
	ds_read_b128 v[210:213], v170 offset:37888
	ds_read_b128 v[214:217], v170 offset:38912
	ds_read_b128 v[218:221], v170 offset:39936
	global_load_lds_dwordx4 v154, s[34:35]
	s_mov_b32 m0, s50
	s_nop 0
	global_load_lds_dwordx4 v156, s[34:35]
	s_waitcnt vmcnt(8)
	s_waitcnt lgkmcnt(0)
	s_barrier
	s_setprio 1
	s_waitcnt lgkmcnt(0)
	v_mfma_f32_16x16x32_bf16 v[122:125], v[126:129], v[180:183], v[122:125]
	v_mfma_f32_16x16x32_bf16 v[114:117], v[138:141], v[180:183], v[114:117]
	v_mfma_f32_16x16x32_bf16 v[106:109], v[126:129], v[198:201], v[106:109]
	v_mfma_f32_16x16x32_bf16 v[98:101], v[138:141], v[198:201], v[98:101]
	v_mfma_f32_16x16x32_bf16 v[90:93], v[126:129], v[206:209], v[90:93]
	v_mfma_f32_16x16x32_bf16 v[82:85], v[138:141], v[206:209], v[82:85]
	v_mfma_f32_16x16x32_bf16 v[74:77], v[126:129], v[214:217], v[74:77]
	v_mfma_f32_16x16x32_bf16 v[66:69], v[138:141], v[214:217], v[66:69]
	v_mfma_f32_16x16x32_bf16 v[122:125], v[134:137], v[184:187], v[122:125]
	v_mfma_f32_16x16x32_bf16 v[114:117], v[142:145], v[184:187], v[114:117]
	v_mfma_f32_16x16x32_bf16 v[106:109], v[134:137], v[202:205], v[106:109]
	v_mfma_f32_16x16x32_bf16 v[98:101], v[142:145], v[202:205], v[98:101]
	v_mfma_f32_16x16x32_bf16 v[90:93], v[134:137], v[210:213], v[90:93]
	v_mfma_f32_16x16x32_bf16 v[82:85], v[142:145], v[210:213], v[82:85]
	v_mfma_f32_16x16x32_bf16 v[74:77], v[134:137], v[218:221], v[74:77]
	v_mfma_f32_16x16x32_bf16 v[66:69], v[142:145], v[218:221], v[66:69]
	s_setprio 0
	s_setprio 1
	v_mfma_f32_16x16x32_bf16 v[130:133], v[146:149], v[180:183], v[130:133]
	v_mfma_f32_16x16x32_bf16 v[118:121], v[172:175], v[180:183], v[118:121]
	v_mfma_f32_16x16x32_bf16 v[110:113], v[146:149], v[198:201], v[110:113]
	v_mfma_f32_16x16x32_bf16 v[102:105], v[172:175], v[198:201], v[102:105]
	v_mfma_f32_16x16x32_bf16 v[94:97], v[146:149], v[206:209], v[94:97]
	v_mfma_f32_16x16x32_bf16 v[86:89], v[172:175], v[206:209], v[86:89]
	v_mfma_f32_16x16x32_bf16 v[78:81], v[146:149], v[214:217], v[78:81]
	v_mfma_f32_16x16x32_bf16 v[70:73], v[172:175], v[214:217], v[70:73]
	v_mfma_f32_16x16x32_bf16 v[130:133], v[150:153], v[184:187], v[130:133]
	v_mfma_f32_16x16x32_bf16 v[118:121], v[176:179], v[184:187], v[118:121]
	v_mfma_f32_16x16x32_bf16 v[110:113], v[150:153], v[202:205], v[110:113]
	v_mfma_f32_16x16x32_bf16 v[102:105], v[176:179], v[202:205], v[102:105]
	v_mfma_f32_16x16x32_bf16 v[94:97], v[150:153], v[210:213], v[94:97]
	v_mfma_f32_16x16x32_bf16 v[86:89], v[176:179], v[210:213], v[86:89]
	v_mfma_f32_16x16x32_bf16 v[78:81], v[150:153], v[218:221], v[78:81]
	v_mfma_f32_16x16x32_bf16 v[70:73], v[176:179], v[218:221], v[70:73]
	s_setprio 0
	s_barrier
	s_add_i32 s100, s55, s36
	s_add_u32 s28, s28, 0x80
	s_addc_u32 s29, s29, 0
	s_mov_b32 m0, s100
	ds_read_b128 v[180:183], v170 offset:49152
	ds_read_b128 v[184:187], v170 offset:50176
	ds_read_b128 v[198:201], v170 offset:51200
	ds_read_b128 v[202:205], v170 offset:52224
	ds_read_b128 v[206:209], v170 offset:53248
	ds_read_b128 v[210:213], v170 offset:54272
	ds_read_b128 v[214:217], v170 offset:55296
	ds_read_b128 v[218:221], v170 offset:56320
	global_load_lds_dwordx4 v48, s[28:29]
	s_add_i32 m0, s100, 0x2000
	s_add_u32 s68, s34, 0xfffc0080
	s_addc_u32 s69, s35, -1
	s_add_i32 s100, s56, s36
	global_load_lds_dwordx4 v158, s[28:29]
	s_add_u32 s28, s28, 0x40000
	s_addc_u32 s29, s29, 0
	s_mov_b32 m0, s100
	s_nop 0
	global_load_lds_dwordx4 v48, s[28:29]
	s_add_i32 m0, s100, 0x2000
	s_nop 0
	global_load_lds_dwordx4 v158, s[28:29]
	s_mov_b32 m0, s52
	s_nop 0
	global_load_lds_dwordx4 v154, s[68:69]
	s_mov_b32 m0, s53
	s_nop 0
	global_load_lds_dwordx4 v156, s[68:69]
	s_waitcnt vmcnt(8)
	s_waitcnt lgkmcnt(0)
	s_barrier
	s_setprio 1
	s_waitcnt lgkmcnt(0)
	v_mfma_f32_16x16x32_bf16 v[58:61], v[126:129], v[180:183], v[58:61]
	v_mfma_f32_16x16x32_bf16 v[50:53], v[138:141], v[180:183], v[50:53]
	v_mfma_f32_16x16x32_bf16 v[40:43], v[126:129], v[198:201], v[40:43]
	v_mfma_f32_16x16x32_bf16 v[32:35], v[138:141], v[198:201], v[32:35]
	v_mfma_f32_16x16x32_bf16 v[24:27], v[126:129], v[206:209], v[24:27]
	v_mfma_f32_16x16x32_bf16 v[16:19], v[138:141], v[206:209], v[16:19]
	v_mfma_f32_16x16x32_bf16 v[8:11], v[126:129], v[214:217], v[8:11]
	v_mfma_f32_16x16x32_bf16 v[0:3], v[138:141], v[214:217], v[0:3]
	v_mfma_f32_16x16x32_bf16 v[58:61], v[134:137], v[184:187], v[58:61]
	v_mfma_f32_16x16x32_bf16 v[50:53], v[142:145], v[184:187], v[50:53]
	v_mfma_f32_16x16x32_bf16 v[40:43], v[134:137], v[202:205], v[40:43]
	v_mfma_f32_16x16x32_bf16 v[32:35], v[142:145], v[202:205], v[32:35]
	v_mfma_f32_16x16x32_bf16 v[24:27], v[134:137], v[210:213], v[24:27]
	v_mfma_f32_16x16x32_bf16 v[16:19], v[142:145], v[210:213], v[16:19]
	v_mfma_f32_16x16x32_bf16 v[8:11], v[134:137], v[218:221], v[8:11]
	v_mfma_f32_16x16x32_bf16 v[0:3], v[142:145], v[218:221], v[0:3]
	s_setprio 0
	s_setprio 1
	v_mfma_f32_16x16x32_bf16 v[62:65], v[146:149], v[180:183], v[62:65]
	v_mfma_f32_16x16x32_bf16 v[54:57], v[172:175], v[180:183], v[54:57]
	v_mfma_f32_16x16x32_bf16 v[44:47], v[146:149], v[198:201], v[44:47]
	v_mfma_f32_16x16x32_bf16 v[36:39], v[172:175], v[198:201], v[36:39]
	v_mfma_f32_16x16x32_bf16 v[28:31], v[146:149], v[206:209], v[28:31]
	v_mfma_f32_16x16x32_bf16 v[20:23], v[172:175], v[206:209], v[20:23]
	v_mfma_f32_16x16x32_bf16 v[12:15], v[146:149], v[214:217], v[12:15]
	v_mfma_f32_16x16x32_bf16 v[4:7], v[172:175], v[214:217], v[4:7]
	v_mfma_f32_16x16x32_bf16 v[62:65], v[150:153], v[184:187], v[62:65]
	v_mfma_f32_16x16x32_bf16 v[54:57], v[176:179], v[184:187], v[54:57]
	v_mfma_f32_16x16x32_bf16 v[44:47], v[150:153], v[202:205], v[44:47]
	v_mfma_f32_16x16x32_bf16 v[36:39], v[176:179], v[202:205], v[36:39]
	v_mfma_f32_16x16x32_bf16 v[28:31], v[150:153], v[210:213], v[28:31]
	v_mfma_f32_16x16x32_bf16 v[20:23], v[176:179], v[210:213], v[20:23]
	v_mfma_f32_16x16x32_bf16 v[12:15], v[150:153], v[218:221], v[12:15]
	v_mfma_f32_16x16x32_bf16 v[4:7], v[176:179], v[218:221], v[4:7]
	s_setprio 0
	s_barrier
	s_add_i32 s54, s54, 2
	s_add_u32 s30, s30, 0x100
	s_addc_u32 s31, s31, 0
	s_add_u32 s45, s45, 0x100
	s_addc_u32 s46, s46, 0
	s_cmp_gt_u32 s54, 13
	s_cbranch_scc0 .LBB0_158
	s_and_b64 vcc, exec, s[18:19]
	s_cbranch_vccz .LBB0_161
	s_barrier
